# NA loop PV rewrite (V prefetch ring, tree max, direct negm C operand) + diff epilogue gain loads grouped
# speedup vs baseline: 1.0170x; 1.0042x over previous
; DEV void attn_diff_unit(const Params& p, int l, int bl, int hd, int q_t0, int n_tiles, char* smem) {
;     ...
;   __syncthreads();
;   if (w < 4) {
;     float ss = 0;
; #pragma unroll
;     for (int v = 0; v < 4; ++v)
; #pragma unroll
;       for (int e = 0; e < 16; ++e) {
;         const float t = o[v][e] * linv - lam * xb[(w * 64 + v * 16 + e) * 64 + lane];
;         o[v][e] = t;
;         ss += t * t;
;       }
.LBB0_93:
	s_or_b64 exec, exec, s[0:1]
	v_cmp_gt_i32_e32 vcc, 4, v120
	s_waitcnt lgkmcnt(0)
	s_barrier
	s_and_saveexec_b64 s[0:1], vcc
	s_cbranch_execz .LBB0_50
	v_add3_u32 v132, 0, v64, v65
	ds_read2st64_b32 v[64:65], v132 offset1:1
	ds_read2st64_b32 v[66:67], v132 offset0:2 offset1:3
	ds_read2st64_b32 v[72:73], v132 offset0:4 offset1:5
	ds_read2st64_b32 v[76:77], v132 offset0:6 offset1:7
	v_mov_b32_e32 v70, v33
	v_mov_b32_e32 v71, v34
	v_mov_b32_e32 v34, v35
	v_mov_b32_e32 v35, v32
	s_waitcnt lgkmcnt(2)
	v_mov_b32_e32 v32, v67
	v_mov_b32_e32 v33, v64
	v_pk_mul_f32 v[32:33], v[146:147], v[32:33] op_sel_hi:[0,1]
	v_mov_b32_e32 v74, v65
	v_mov_b32_e32 v75, v66
	v_pk_fma_f32 v[84:85], v[34:35], v[68:69], v[32:33] op_sel_hi:[1,0,1] neg_lo:[0,0,1] neg_hi:[0,0,1]
	s_waitcnt lgkmcnt(1)
	v_mov_b32_e32 v34, v73
	s_waitcnt lgkmcnt(0)
	v_mov_b32_e32 v35, v76
	v_pk_mul_f32 v[74:75], v[146:147], v[74:75] op_sel_hi:[0,1]
	v_mov_b32_e32 v32, v37
	v_mov_b32_e32 v33, v38
	v_pk_mul_f32 v[34:35], v[146:147], v[34:35] op_sel_hi:[0,1]
	v_pk_fma_f32 v[82:83], v[70:71], v[68:69], v[74:75] op_sel_hi:[1,0,1] neg_lo:[0,0,1] neg_hi:[0,0,1]
	v_pk_fma_f32 v[74:75], v[32:33], v[68:69], v[34:35] op_sel_hi:[1,0,1] neg_lo:[0,0,1] neg_hi:[0,0,1]
	v_mov_b32_e32 v34, v77
	v_mov_b32_e32 v35, v72
	v_mov_b32_e32 v32, v39
	v_mov_b32_e32 v33, v36
	v_pk_mul_f32 v[34:35], v[146:147], v[34:35] op_sel_hi:[0,1]
	v_pk_fma_f32 v[76:77], v[32:33], v[68:69], v[34:35] op_sel_hi:[1,0,1] neg_lo:[0,0,1] neg_hi:[0,0,1]
	ds_read2st64_b32 v[32:33], v132 offset0:8 offset1:9
	ds_read2st64_b32 v[34:35], v132 offset0:10 offset1:11
	ds_read2st64_b32 v[38:39], v132 offset0:12 offset1:13
	ds_read2st64_b32 v[64:65], v132 offset0:14 offset1:15
	v_mov_b32_e32 v36, v41
	v_mov_b32_e32 v37, v42
	s_waitcnt lgkmcnt(3)
	v_mov_b32_e32 v66, v33
	s_waitcnt lgkmcnt(2)
	v_mov_b32_e32 v67, v34
	v_pk_mul_f32 v[66:67], v[146:147], v[66:67] op_sel_hi:[0,1]
	v_mov_b32_e32 v34, v35
	v_mov_b32_e32 v35, v32
	v_pk_fma_f32 v[78:79], v[36:37], v[68:69], v[66:67] op_sel_hi:[1,0,1] neg_lo:[0,0,1] neg_hi:[0,0,1]
	v_mov_b32_e32 v36, v43
	v_mov_b32_e32 v37, v40
	v_pk_mul_f32 v[32:33], v[146:147], v[34:35] op_sel_hi:[0,1]
	s_waitcnt lgkmcnt(1)
	v_mov_b32_e32 v34, v39
	s_waitcnt lgkmcnt(0)
	v_mov_b32_e32 v35, v64
	v_pk_fma_f32 v[80:81], v[36:37], v[68:69], v[32:33] op_sel_hi:[1,0,1] neg_lo:[0,0,1] neg_hi:[0,0,1]
	v_mov_b32_e32 v32, v45
	v_mov_b32_e32 v33, v46
	v_pk_mul_f32 v[34:35], v[146:147], v[34:35] op_sel_hi:[0,1]
	v_pk_fma_f32 v[70:71], v[32:33], v[68:69], v[34:35] op_sel_hi:[1,0,1] neg_lo:[0,0,1] neg_hi:[0,0,1]
	v_mov_b32_e32 v34, v65
	v_mov_b32_e32 v35, v38
	v_mov_b32_e32 v32, v47
	v_mov_b32_e32 v33, v44
	v_pk_mul_f32 v[34:35], v[146:147], v[34:35] op_sel_hi:[0,1]
	v_pk_fma_f32 v[72:73], v[32:33], v[68:69], v[34:35] op_sel_hi:[1,0,1] neg_lo:[0,0,1] neg_hi:[0,0,1]
	ds_read2st64_b32 v[32:33], v132 offset0:16 offset1:17
	ds_read2st64_b32 v[34:35], v132 offset0:18 offset1:19
	ds_read2st64_b32 v[38:39], v132 offset0:20 offset1:21
	ds_read2st64_b32 v[40:41], v132 offset0:22 offset1:23
	v_mov_b32_e32 v36, v49
	v_mov_b32_e32 v37, v50
	s_waitcnt lgkmcnt(3)
	v_mov_b32_e32 v42, v33
	s_waitcnt lgkmcnt(2)
	v_mov_b32_e32 v43, v34
	v_pk_mul_f32 v[42:43], v[146:147], v[42:43] op_sel_hi:[0,1]
	v_mov_b32_e32 v34, v35
	v_mov_b32_e32 v35, v32
	v_pk_fma_f32 v[64:65], v[36:37], v[68:69], v[42:43] op_sel_hi:[1,0,1] neg_lo:[0,0,1] neg_hi:[0,0,1]
	v_mov_b32_e32 v36, v51
	v_mov_b32_e32 v37, v48
	v_pk_mul_f32 v[32:33], v[146:147], v[34:35] op_sel_hi:[0,1]
	s_waitcnt lgkmcnt(1)
	v_mov_b32_e32 v34, v39
	s_waitcnt lgkmcnt(0)
	v_mov_b32_e32 v35, v40
	v_pk_fma_f32 v[66:67], v[36:37], v[68:69], v[32:33] op_sel_hi:[1,0,1] neg_lo:[0,0,1] neg_hi:[0,0,1]
	v_mov_b32_e32 v32, v53
	v_mov_b32_e32 v33, v54
	v_pk_mul_f32 v[34:35], v[146:147], v[34:35] op_sel_hi:[0,1]
	v_pk_fma_f32 v[46:47], v[32:33], v[68:69], v[34:35] op_sel_hi:[1,0,1] neg_lo:[0,0,1] neg_hi:[0,0,1]
	v_mov_b32_e32 v34, v41
	v_mov_b32_e32 v35, v38
	v_mov_b32_e32 v32, v55
	v_mov_b32_e32 v33, v52
	v_pk_mul_f32 v[34:35], v[146:147], v[34:35] op_sel_hi:[0,1]
	v_pk_fma_f32 v[48:49], v[32:33], v[68:69], v[34:35] op_sel_hi:[1,0,1] neg_lo:[0,0,1] neg_hi:[0,0,1]
	ds_read2st64_b32 v[32:33], v132 offset0:24 offset1:25
	ds_read2st64_b32 v[34:35], v132 offset0:26 offset1:27
	ds_read2st64_b32 v[38:39], v132 offset0:28 offset1:29
	ds_read2st64_b32 v[40:41], v132 offset0:30 offset1:31
	v_mov_b32_e32 v36, v57
	v_mov_b32_e32 v37, v58
	s_waitcnt lgkmcnt(3)
	v_mov_b32_e32 v42, v33
	s_waitcnt lgkmcnt(2)
	v_mov_b32_e32 v43, v34
	v_pk_mul_f32 v[42:43], v[146:147], v[42:43] op_sel_hi:[0,1]
	v_mov_b32_e32 v34, v35
	v_mov_b32_e32 v35, v32
	v_pk_fma_f32 v[50:51], v[36:37], v[68:69], v[42:43] op_sel_hi:[1,0,1] neg_lo:[0,0,1] neg_hi:[0,0,1]
	v_mov_b32_e32 v36, v59
	v_mov_b32_e32 v37, v56
	v_pk_mul_f32 v[32:33], v[146:147], v[34:35] op_sel_hi:[0,1]
	s_waitcnt lgkmcnt(1)
	v_mov_b32_e32 v34, v39
	s_waitcnt lgkmcnt(0)
	v_mov_b32_e32 v35, v40
	v_pk_fma_f32 v[52:53], v[36:37], v[68:69], v[32:33] op_sel_hi:[1,0,1] neg_lo:[0,0,1] neg_hi:[0,0,1]
	v_mov_b32_e32 v32, v61
	v_mov_b32_e32 v33, v62
	v_pk_mul_f32 v[34:35], v[146:147], v[34:35] op_sel_hi:[0,1]
	v_pk_fma_f32 v[42:43], v[32:33], v[68:69], v[34:35] op_sel_hi:[1,0,1] neg_lo:[0,0,1] neg_hi:[0,0,1]
	v_mov_b32_e32 v34, v41
	v_mov_b32_e32 v35, v38
	v_mov_b32_e32 v32, v63
	v_mov_b32_e32 v33, v60
	v_pk_mul_f32 v[34:35], v[146:147], v[34:35] op_sel_hi:[0,1]
	v_pk_fma_f32 v[44:45], v[32:33], v[68:69], v[34:35] op_sel_hi:[1,0,1] neg_lo:[0,0,1] neg_hi:[0,0,1]
	ds_read2st64_b32 v[32:33], v132 offset0:32 offset1:33
	ds_read2st64_b32 v[34:35], v132 offset0:34 offset1:35
	ds_read2st64_b32 v[114:115], v132 offset0:36 offset1:37
	ds_read2st64_b32 v[116:117], v132 offset0:38 offset1:39
	v_mov_b32_e32 v36, v17
	v_mov_b32_e32 v37, v18
	v_mov_b32_e32 v18, v19
	v_mov_b32_e32 v19, v16
	s_waitcnt lgkmcnt(2)
; DEV int opaque_tid() { int t = threadIdx.x; asm volatile("" : "+v"(t)); return t; }
; DEV float xor32(float v) { return __shfl_xor(v, 32, 64); }
; template <int NV>
; DEV void attn_store(f32x16 (&o)[NV], float scale_lane, const u16* zrow, u16* arow, const float* vgain  ) {
;   const int lane = opaque_tid() & 63, h = lane >> 5;
; #pragma unroll
;   for (int v = 0; v < NV; ++v) {
;     float ov[16];
; #pragma unroll
;     for (int g4 = 0; g4 < 4; ++g4) {
;       const int f = 32 * v + 8 * g4 + 4 * h;
;       const uint2 zz = *(const uint2*)(zrow + f);
;       float z0 = __uint_as_float(zz.x << 16), z1 = __uint_as_float(zz.x & 0xffff0000u);
;       float z2 = __uint_as_float(zz.y << 16), z3 = __uint_as_float(zz.y & 0xffff0000u);
; DEV void attn_diff_unit(const Params& p, int l, int bl, int hd, int q_t0, int n_tiles, char* smem) {
;     ...
;   if (w < 4) {
;     float ss = 0;
; #pragma unroll
;     for (int v = 0; v < 4; ++v)
; #pragma unroll
;       for (int e = 0; e < 16; ++e) {
;         const float t = o[v][e] * linv - lam * xb[(w * 64 + v * 16 + e) * 64 + lane];
;         o[v][e] = t;
;         ss += t * t;
;       }
;     ss += xor32(ss);
;     const float rs = rsqrtf(ss * (1.f / 128.f) + EPS) * (1.f - lam_init);
;     const int tp = q_t0 + w * 32 + r;
;     const size_t m = (size_t)bl * TP + tp;
;     attn_store<4>(o, rs, (const u16*)(ws + OFF_Z) + m * 1536 + 1024 + hd * 128, (u16*)(ws + OFF_ACAT) + m * 1536 + 1024 + hd * 128,
;                   p.diff_subln_g + l * 128);
	v_mov_b32_e32 v16, v35
	v_mov_b32_e32 v17, v32
	v_pk_mul_f32 v[16:17], v[146:147], v[16:17] op_sel_hi:[0,1]
	v_pk_fma_f32 v[40:41], v[18:19], v[68:69], v[16:17] op_sel_hi:[1,0,1] neg_lo:[0,0,1] neg_hi:[0,0,1]
	s_waitcnt lgkmcnt(1)
	v_mov_b32_e32 v18, v115
	s_waitcnt lgkmcnt(0)
	v_mov_b32_e32 v19, v116
	v_mov_b32_e32 v16, v21
	v_mov_b32_e32 v17, v22
	v_pk_mul_f32 v[18:19], v[146:147], v[18:19] op_sel_hi:[0,1]
	v_mov_b32_e32 v38, v33
	v_pk_fma_f32 v[32:33], v[16:17], v[68:69], v[18:19] op_sel_hi:[1,0,1] neg_lo:[0,0,1] neg_hi:[0,0,1]
	v_mov_b32_e32 v18, v117
	v_mov_b32_e32 v19, v114
	v_mov_b32_e32 v16, v23
	v_mov_b32_e32 v17, v20
	v_pk_mul_f32 v[18:19], v[146:147], v[18:19] op_sel_hi:[0,1]
	v_mov_b32_e32 v39, v34
	v_pk_fma_f32 v[34:35], v[16:17], v[68:69], v[18:19] op_sel_hi:[1,0,1] neg_lo:[0,0,1] neg_hi:[0,0,1]
	ds_read2st64_b32 v[16:17], v132 offset0:40 offset1:41
	ds_read2st64_b32 v[18:19], v132 offset0:42 offset1:43
	ds_read2st64_b32 v[122:123], v132 offset0:44 offset1:45
	ds_read2st64_b32 v[124:125], v132 offset0:46 offset1:47
	v_pk_mul_f32 v[38:39], v[146:147], v[38:39] op_sel_hi:[0,1]
	v_pk_fma_f32 v[38:39], v[36:37], v[68:69], v[38:39] op_sel_hi:[1,0,1] neg_lo:[0,0,1] neg_hi:[0,0,1]
	s_waitcnt lgkmcnt(3)
	v_mov_b32_e32 v36, v17
	s_waitcnt lgkmcnt(2)
	v_mov_b32_e32 v37, v18
	v_mov_b32_e32 v22, v25
	v_mov_b32_e32 v23, v26
	v_pk_mul_f32 v[36:37], v[146:147], v[36:37] op_sel_hi:[0,1]
	v_mov_b32_e32 v18, v19
	v_mov_b32_e32 v19, v16
	v_pk_fma_f32 v[36:37], v[22:23], v[68:69], v[36:37] op_sel_hi:[1,0,1] neg_lo:[0,0,1] neg_hi:[0,0,1]
	v_mov_b32_e32 v22, v27
	v_mov_b32_e32 v23, v24
	v_pk_mul_f32 v[16:17], v[146:147], v[18:19] op_sel_hi:[0,1]
	s_waitcnt lgkmcnt(1)
	v_mov_b32_e32 v18, v123
	s_waitcnt lgkmcnt(0)
	v_mov_b32_e32 v19, v124
	v_pk_fma_f32 v[26:27], v[22:23], v[68:69], v[16:17] op_sel_hi:[1,0,1] neg_lo:[0,0,1] neg_hi:[0,0,1]
	v_mov_b32_e32 v16, v29
	v_mov_b32_e32 v17, v30
	v_pk_mul_f32 v[18:19], v[146:147], v[18:19] op_sel_hi:[0,1]
	v_pk_fma_f32 v[22:23], v[16:17], v[68:69], v[18:19] op_sel_hi:[1,0,1] neg_lo:[0,0,1] neg_hi:[0,0,1]
	v_mov_b32_e32 v18, v125
	v_mov_b32_e32 v19, v122
	v_mov_b32_e32 v16, v31
	v_mov_b32_e32 v17, v28
	v_pk_mul_f32 v[18:19], v[146:147], v[18:19] op_sel_hi:[0,1]
	v_pk_fma_f32 v[24:25], v[16:17], v[68:69], v[18:19] op_sel_hi:[1,0,1] neg_lo:[0,0,1] neg_hi:[0,0,1]
	ds_read2st64_b32 v[16:17], v132 offset0:48 offset1:49
	ds_read2st64_b32 v[18:19], v132 offset0:50 offset1:51
	ds_read2st64_b32 v[28:29], v132 offset0:52 offset1:53
	ds_read2st64_b32 v[30:31], v132 offset0:54 offset1:55
	v_pk_mul_f32 v[94:95], v[82:83], v[82:83]
	v_pk_mul_f32 v[96:97], v[84:85], v[84:85]
	v_pk_mul_f32 v[106:107], v[76:77], v[76:77]
	s_waitcnt lgkmcnt(3)
	v_pk_mul_f32 v[16:17], v[146:147], v[16:17] op_sel_hi:[0,1]
	v_pk_fma_f32 v[16:17], v[0:1], v[68:69], v[16:17] op_sel_hi:[1,0,1] neg_lo:[0,0,1] neg_hi:[0,0,1]
	s_waitcnt lgkmcnt(2)
	v_pk_mul_f32 v[0:1], v[146:147], v[18:19] op_sel_hi:[0,1]
	v_pk_fma_f32 v[18:19], v[2:3], v[68:69], v[0:1] op_sel_hi:[1,0,1] neg_lo:[0,0,1] neg_hi:[0,0,1]
	s_waitcnt lgkmcnt(1)
	v_pk_mul_f32 v[0:1], v[146:147], v[28:29] op_sel_hi:[0,1]
	v_pk_fma_f32 v[0:1], v[4:5], v[68:69], v[0:1] op_sel_hi:[1,0,1] neg_lo:[0,0,1] neg_hi:[0,0,1]
	s_waitcnt lgkmcnt(0)
	v_pk_mul_f32 v[2:3], v[146:147], v[30:31] op_sel_hi:[0,1]
	ds_read2st64_b32 v[4:5], v132 offset0:56 offset1:57
	v_pk_fma_f32 v[2:3], v[6:7], v[68:69], v[2:3] op_sel_hi:[1,0,1] neg_lo:[0,0,1] neg_hi:[0,0,1]
	ds_read2st64_b32 v[6:7], v132 offset0:58 offset1:59
	ds_read2st64_b32 v[28:29], v132 offset0:60 offset1:61
	ds_read2st64_b32 v[30:31], v132 offset0:62 offset1:63
	v_pk_mul_f32 v[102:103], v[74:75], v[74:75]
	v_pk_mul_f32 v[88:89], v[80:81], v[80:81]
	s_waitcnt lgkmcnt(3)
	v_pk_mul_f32 v[4:5], v[146:147], v[4:5] op_sel_hi:[0,1]
	v_pk_fma_f32 v[8:9], v[8:9], v[68:69], v[4:5] op_sel_hi:[1,0,1] neg_lo:[0,0,1] neg_hi:[0,0,1]
	s_waitcnt lgkmcnt(2)
	v_pk_mul_f32 v[4:5], v[146:147], v[6:7] op_sel_hi:[0,1]
	s_waitcnt lgkmcnt(1)
	v_mov_b32_e32 v6, v29
	s_waitcnt lgkmcnt(0)
	v_mov_b32_e32 v7, v30
	v_pk_fma_f32 v[10:11], v[10:11], v[68:69], v[4:5] op_sel_hi:[1,0,1] neg_lo:[0,0,1] neg_hi:[0,0,1]
	v_mov_b32_e32 v4, v13
	v_mov_b32_e32 v5, v14
	v_pk_mul_f32 v[6:7], v[146:147], v[6:7] op_sel_hi:[0,1]
	v_pk_fma_f32 v[4:5], v[4:5], v[68:69], v[6:7] op_sel_hi:[1,0,1] neg_lo:[0,0,1] neg_hi:[0,0,1]
	v_mov_b32_e32 v7, v12
	v_mov_b32_e32 v12, v31
	v_mov_b32_e32 v13, v28
	v_mov_b32_e32 v6, v15
	v_pk_mul_f32 v[12:13], v[146:147], v[12:13] op_sel_hi:[0,1]
	v_pk_fma_f32 v[6:7], v[6:7], v[68:69], v[12:13] op_sel_hi:[1,0,1] neg_lo:[0,0,1] neg_hi:[0,0,1]
	v_pk_mul_f32 v[86:87], v[78:79], v[78:79]
	v_pk_mov_b32 v[14:15], v[4:5], v[6:7] op_sel:[1,0]
	v_and_b32_e32 v121, 31, v182
	v_pk_mul_f32 v[136:137], v[14:15], v[14:15]
	v_add_f32_e32 v14, v97, v94
	v_add_f32_e32 v14, v14, v95
	v_add_f32_e32 v14, v14, v96
	v_add_f32_e32 v14, v14, v107
	v_add_f32_e32 v14, v14, v102
	v_add_f32_e32 v14, v14, v103
	v_add_f32_e32 v14, v14, v106
	v_add_f32_e32 v14, v14, v89
	v_add_f32_e32 v68, v14, v86
	v_lshlrev_b32_e32 v14, 5, v120
	v_add3_u32 v14, v121, s9, v14
	s_mul_i32 s34, s10, 0x2100
	v_ashrrev_i32_e32 v15, 31, v14
	v_lshl_add_u64 v[14:15], v[14:15], 0, s[34:35]
	v_mov_b64_e32 v[28:29], s[38:39]
	v_mad_u64_u32 v[28:29], s[2:3], v14, s47, v[28:29]
	v_mov_b32_e32 v30, v147
	v_mad_i32_i24 v29, v15, s47, v29
	s_lshl_b32 s34, s8, 8
	v_lshl_add_u64 v[14:15], v[28:29], 0, s[34:35]
	v_bfe_u32 v86, v30, 5, 1
	v_lshlrev_b32_e32 v144, 3, v86
	v_lshl_add_u64 v[14:15], v[14:15], 0, v[144:145]
	v_add_co_u32_e32 v30, vcc, 0xee56000, v14
	v_add_f32_e32 v68, v68, v87
	s_nop 0
	v_addc_co_u32_e32 v31, vcc, 0, v15, vcc
; DEV int opaque_tid() { int t = threadIdx.x; asm volatile("" : "+v"(t)); return t; }
; DEV float xor32(float v) { return __shfl_xor(v, 32, 64); }
; template <int NV>
; DEV void attn_store(f32x16 (&o)[NV], float scale_lane, const u16* zrow, u16* arow, const float* vgain  ) {
;   const int lane = opaque_tid() & 63, h = lane >> 5;
; #pragma unroll
;   for (int v = 0; v < NV; ++v) {
;     float ov[16];
; #pragma unroll
;     for (int g4 = 0; g4 < 4; ++g4) {
;       const int f = 32 * v + 8 * g4 + 4 * h;
;       const uint2 zz = *(const uint2*)(zrow + f);
;       float z0 = __uint_as_float(zz.x << 16), z1 = __uint_as_float(zz.x & 0xffff0000u);
;       float z2 = __uint_as_float(zz.y << 16), z3 = __uint_as_float(zz.y & 0xffff0000u);
;       float a0 = o[v][4 * g4] * scale_lane, a1 = o[v][4 * g4 + 1] * scale_lane, a2 = o[v][4 * g4 + 2] * scale_lane,
;             a3 = o[v][4 * g4 + 3] * scale_lane;
;       if (vgain) {
;         const float4 gg = *(const float4*)(vgain + f);
;         a0 *= gg.x; a1 *= gg.y; a2 *= gg.z; a3 *= gg.w;
;       }
;       ov[4 * g4] = a0 * z0; ov[4 * g4 + 1] = a1 * z1; ov[4 * g4 + 2] = a2 * z2; ov[4 * g4 + 3] = a3 * z3;
;     }
;     store_row32(arow + 32 * v, ov, h);
; DEV void attn_diff_unit(const Params& p, int l, int bl, int hd, int q_t0, int n_tiles, char* smem) {
;     ...
;     ss += xor32(ss);
;     const float rs = rsqrtf(ss * (1.f / 128.f) + EPS) * (1.f - lam_init);
;     const int tp = q_t0 + w * 32 + r;
;     const size_t m = (size_t)bl * TP + tp;
;     attn_store<4>(o, rs, (const u16*)(ws + OFF_Z) + m * 1536 + 1024 + hd * 128, (u16*)(ws + OFF_ACAT) + m * 1536 + 1024 + hd * 128,
;                   p.diff_subln_g + l * 128);
	flat_load_dwordx2 v[30:31], v[30:31] offset:2304
	v_pk_mul_f32 v[92:93], v[72:73], v[72:73]
	v_add_f32_e32 v68, v68, v88
	v_pk_mul_f32 v[90:91], v[70:71], v[70:71]
	v_add_f32_e32 v68, v68, v93
	v_add_f32_e32 v68, v68, v90
	v_add_f32_e32 v68, v68, v91
	v_pk_mul_f32 v[100:101], v[66:67], v[66:67]
	v_add_f32_e32 v68, v68, v92
	v_pk_mul_f32 v[98:99], v[64:65], v[64:65]
	v_add_f32_e32 v68, v68, v101
	v_add_f32_e32 v68, v68, v98
	v_add_f32_e32 v68, v68, v99
	v_pk_mul_f32 v[54:55], v[48:49], v[48:49]
	v_add_f32_e32 v68, v68, v100
	v_pk_mul_f32 v[104:105], v[46:47], v[46:47]
	v_add_f32_e32 v55, v68, v55
	v_add_f32_e32 v55, v55, v104
	v_add_f32_e32 v55, v55, v105
	v_pk_mul_f32 v[56:57], v[52:53], v[52:53]
	v_add_f32_e32 v54, v55, v54
	v_pk_mul_f32 v[108:109], v[50:51], v[50:51]
	v_add_f32_e32 v54, v54, v57
	v_add_f32_e32 v54, v54, v108
	v_add_f32_e32 v54, v54, v109
	v_pk_mul_f32 v[60:61], v[44:45], v[44:45]
	v_add_f32_e32 v54, v54, v56
	v_pk_mul_f32 v[58:59], v[42:43], v[42:43]
	v_add_f32_e32 v54, v54, v61
	v_add_f32_e32 v54, v54, v58
	v_add_f32_e32 v54, v54, v59
	v_pk_mul_f32 v[110:111], v[40:41], v[40:41]
	v_add_f32_e32 v54, v54, v60
	v_pk_mul_f32 v[62:63], v[38:39], v[38:39]
	v_add_f32_e32 v54, v54, v111
	v_add_f32_e32 v54, v54, v62
	v_add_f32_e32 v54, v54, v63
	v_pk_mul_f32 v[20:21], v[34:35], v[34:35]
	v_add_f32_e32 v54, v54, v110
	v_pk_mul_f32 v[112:113], v[32:33], v[32:33]
	v_add_f32_e32 v21, v54, v21
	v_add_f32_e32 v21, v21, v112
	v_add_f32_e32 v21, v21, v113
	v_pk_mul_f32 v[116:117], v[26:27], v[26:27]
	v_add_f32_e32 v20, v21, v20
	v_pk_mul_f32 v[114:115], v[36:37], v[36:37]
	v_add_f32_e32 v20, v20, v117
	v_add_f32_e32 v20, v20, v114
	v_add_f32_e32 v20, v20, v115
	v_pk_mul_f32 v[122:123], v[24:25], v[24:25]
	v_add_f32_e32 v20, v20, v116
	v_pk_mul_f32 v[118:119], v[22:23], v[22:23]
	v_add_f32_e32 v20, v20, v123
	v_add_f32_e32 v20, v20, v118
	v_add_f32_e32 v20, v20, v119
	v_pk_mul_f32 v[124:125], v[16:17], v[16:17]
	v_add_f32_e32 v20, v20, v122
	v_add_f32_e32 v20, v20, v124
	v_pk_mul_f32 v[126:127], v[18:19], v[18:19]
	v_add_f32_e32 v20, v20, v125
	v_add_f32_e32 v20, v20, v126
	v_pk_mul_f32 v[128:129], v[0:1], v[0:1]
	v_add_f32_e32 v20, v20, v127
	v_add_f32_e32 v20, v20, v128
	v_pk_mul_f32 v[130:131], v[2:3], v[2:3]
	v_add_f32_e32 v20, v20, v129
	v_add_f32_e32 v20, v20, v130
	v_pk_mul_f32 v[132:133], v[8:9], v[8:9]
	v_add_f32_e32 v20, v20, v131
	v_add_f32_e32 v20, v20, v132
	v_pk_mul_f32 v[134:135], v[10:11], v[10:11]
	v_add_f32_e32 v20, v20, v133
	v_pk_mov_b32 v[12:13], v[6:7], v[4:5] op_sel:[1,0]
	v_add_f32_e32 v20, v20, v134
	v_pk_mul_f32 v[12:13], v[12:13], v[12:13]
	v_add_f32_e32 v20, v20, v135
	v_add_f32_e32 v12, v20, v12
	v_add_f32_e32 v12, v12, v13
	v_add_f32_e32 v12, v12, v136
	v_add_f32_e32 v12, v12, v137
	ds_bpermute_b32 v13, v69, v12
	v_readlane_b32 s2, v242, 28
	v_readlane_b32 s3, v242, 29
	s_waitcnt lgkmcnt(0)
	v_add_f32_e32 v12, v12, v13
	v_fmamk_f32 v12, v12, 0x3c000000, v169
	v_mul_f32_e32 v13, 0x4b800000, v12
	v_cmp_gt_f32_e32 vcc, s46, v12
	v_cndmask_b32_e64 v56, 0, 1, s[2:3]
	v_cmp_ne_u32_e64 s[38:39], 1, v56
	v_cndmask_b32_e32 v12, v12, v13, vcc
	v_rsq_f32_e32 v12, v12
	s_nop 0
	v_mul_f32_e32 v13, 0x45800000, v12
	v_cndmask_b32_e32 v12, v12, v13, vcc
	v_sub_f32_e32 v13, 1.0, v181
	v_mul_f32_e32 v12, v13, v12
	v_lshlrev_b32_e32 v13, 2, v86
	v_pk_mul_f32 v[20:21], v[82:83], v[12:13] op_sel_hi:[1,0]
	v_pk_mul_f32 v[54:55], v[84:85], v[12:13] op_sel_hi:[1,0]
	v_lshlrev_b32_e32 v82, 2, v13
	s_and_b64 vcc, exec, s[38:39]
	s_cbranch_vccnz .Ldiff_epi_a
	global_load_dwordx4 v[212:215], v82, s[42:43]
	global_load_dwordx4 v[216:219], v82, s[42:43] offset:32
	global_load_dwordx4 v[220:223], v82, s[42:43] offset:64
	global_load_dwordx4 v[224:227], v82, s[42:43] offset:96
	global_load_dwordx4 v[228:231], v82, s[42:43] offset:128
	global_load_dwordx4 v[232:235], v82, s[42:43] offset:160
	global_load_dwordx4 v[236:239], v82, s[42:43] offset:192
	global_load_dwordx4 v[244:247], v82, s[42:43] offset:224
.Ldiff_epi_a:
	s_andn2_b64 vcc, exec, s[2:3]
	s_cbranch_vccnz .LBB0_96
	s_waitcnt vmcnt(0)
	v_mov_b32_e32 v60, v213
	v_mov_b32_e32 v61, v214
	v_mov_b32_e32 v58, v215
	v_mov_b32_e32 v59, v212
	v_pk_mul_f32 v[20:21], v[20:21], v[60:61]
	v_pk_mul_f32 v[54:55], v[54:55], v[58:59]
.LBB0_96:
	s_mov_b64 s[2:3], 0xee56900
	v_lshl_add_u64 v[14:15], v[14:15], 0, s[2:3]
	flat_load_dwordx2 v[58:59], v[14:15] offset:16
	v_mov_b32_e32 v13, v12
	v_pk_mul_f32 v[56:57], v[74:75], v[12:13]
	s_and_b64 vcc, exec, s[38:39]
	v_pk_mul_f32 v[60:61], v[76:77], v[12:13]
	s_cbranch_vccnz .LBB0_98
	v_mov_b32_e32 v62, v217
	v_mov_b32_e32 v63, v218
	v_pk_mul_f32 v[56:57], v[56:57], v[62:63]
	v_mov_b32_e32 v62, v219
	v_mov_b32_e32 v63, v216
	v_pk_mul_f32 v[60:61], v[60:61], v[62:63]
.LBB0_98:
	flat_load_dwordx2 v[68:69], v[14:15] offset:32
	v_pk_mul_f32 v[62:63], v[78:79], v[12:13]
	s_and_b64 vcc, exec, s[38:39]
	v_pk_mul_f32 v[74:75], v[80:81], v[12:13]
	s_cbranch_vccnz .LBB0_100
	v_mov_b32_e32 v80, v221
	v_mov_b32_e32 v81, v222
	v_mov_b32_e32 v78, v223
	v_mov_b32_e32 v79, v220
	v_pk_mul_f32 v[62:63], v[62:63], v[80:81]
	v_pk_mul_f32 v[74:75], v[74:75], v[78:79]
.LBB0_100:
	flat_load_dwordx2 v[76:77], v[14:15] offset:48
	v_pk_mul_f32 v[70:71], v[70:71], v[12:13]
	s_and_b64 vcc, exec, s[38:39]
	v_pk_mul_f32 v[72:73], v[72:73], v[12:13]
	s_cbranch_vccnz .LBB0_102
	v_mov_b32_e32 v84, v225
	v_mov_b32_e32 v85, v226
	v_mov_b32_e32 v80, v227
	v_mov_b32_e32 v81, v224
	v_pk_mul_f32 v[70:71], v[70:71], v[84:85]
	v_pk_mul_f32 v[72:73], v[72:73], v[80:81]
; DEV int opaque_tid() { int t = threadIdx.x; asm volatile("" : "+v"(t)); return t; }
; template <int NV>
; DEV void attn_store(f32x16 (&o)[NV], float scale_lane, const u16* zrow, u16* arow, const float* vgain  ) {
;   const int lane = opaque_tid() & 63, h = lane >> 5;
; #pragma unroll
;   for (int v = 0; v < NV; ++v) {
;     float ov[16];
; #pragma unroll
;     for (int g4 = 0; g4 < 4; ++g4) {
;       const int f = 32 * v + 8 * g4 + 4 * h;
;       const uint2 zz = *(const uint2*)(zrow + f);
;       float z0 = __uint_as_float(zz.x << 16), z1 = __uint_as_float(zz.x & 0xffff0000u);
;       float z2 = __uint_as_float(zz.y << 16), z3 = __uint_as_float(zz.y & 0xffff0000u);
;       float a0 = o[v][4 * g4] * scale_lane, a1 = o[v][4 * g4 + 1] * scale_lane, a2 = o[v][4 * g4 + 2] * scale_lane,
;             a3 = o[v][4 * g4 + 3] * scale_lane;
;       if (vgain) {
;         const float4 gg = *(const float4*)(vgain + f);
;         a0 *= gg.x; a1 *= gg.y; a2 *= gg.z; a3 *= gg.w;
;       }
;       ov[4 * g4] = a0 * z0; ov[4 * g4 + 1] = a1 * z1; ov[4 * g4 + 2] = a2 * z2; ov[4 * g4 + 3] = a3 * z3;
;     }
;     store_row32(arow + 32 * v, ov, h);
.LBB0_102:
	s_waitcnt vmcnt(0) lgkmcnt(0)
	v_lshlrev_b32_e32 v78, 16, v68
	v_and_b32_e32 v79, 0xffff0000, v68
	v_lshlrev_b32_e32 v68, 16, v69
	v_and_b32_e32 v69, 0xffff0000, v69
	v_pk_mov_b32 v[80:81], v[74:75], v[62:63] op_sel:[1,0]
	v_pk_mov_b32 v[62:63], v[62:63], v[74:75] op_sel:[1,0]
	s_lshl_b32 s2, s8, 7
	v_pk_mul_f32 v[78:79], v[80:81], v[78:79]
	v_pk_mul_f32 v[62:63], v[62:63], v[68:69]
	v_lshlrev_b32_e32 v68, 16, v76
	v_and_b32_e32 v69, 0xffff0000, v76
	v_lshlrev_b32_e32 v74, 16, v77
	v_and_b32_e32 v75, 0xffff0000, v77
	v_lshlrev_b32_e32 v76, 16, v58
	v_and_b32_e32 v77, 0xffff0000, v58
	v_lshlrev_b32_e32 v58, 16, v59
	v_and_b32_e32 v59, 0xffff0000, v59
	v_pk_mov_b32 v[80:81], v[60:61], v[56:57] op_sel:[1,0]
	v_pk_mov_b32 v[56:57], v[56:57], v[60:61] op_sel:[1,0]
	v_pk_mov_b32 v[60:61], v[54:55], v[20:21] op_sel:[1,0]
	v_pk_mul_f32 v[56:57], v[56:57], v[58:59]
	v_lshlrev_b32_e32 v58, 16, v30
	v_and_b32_e32 v59, 0xffff0000, v30
	v_lshlrev_b32_e32 v30, 16, v31
	v_and_b32_e32 v31, 0xffff0000, v31
	v_pk_mov_b32 v[20:21], v[20:21], v[54:55] op_sel:[1,0]
	s_lshl_b32 s34, s2, 1
	v_pk_mul_f32 v[30:31], v[20:21], v[30:31]
	v_lshl_add_u64 v[20:21], v[28:29], 0, s[34:35]
	v_lshlrev_b32_e32 v144, 4, v86
	v_pk_mov_b32 v[28:29], v[72:73], v[70:71] op_sel:[1,0]
	v_pk_mul_f32 v[76:77], v[80:81], v[76:77]
	v_pk_mul_f32 v[58:59], v[60:61], v[58:59]
	v_lshl_add_u64 v[60:61], v[20:21], 0, v[144:145]
	v_pk_mul_f32 v[68:69], v[28:29], v[68:69]
	v_pk_mov_b32 v[28:29], v[70:71], v[72:73] op_sel:[1,0]
	s_mov_b64 s[2:3], 0x1c4d6900
	v_pk_mul_f32 v[70:71], v[28:29], v[74:75]
	v_cvt_pk_bf16_f32 v28, v58, v59
	v_cvt_pk_bf16_f32 v29, v30, v31
	v_cvt_pk_bf16_f32 v30, v76, v77
	v_cvt_pk_bf16_f32 v31, v56, v57
	v_add_co_u32_e32 v58, vcc, 0x1c4d6000, v60
	v_permlane32_swap_b32_e32 v28, v30
	v_permlane32_swap_b32_e32 v29, v31
	v_addc_co_u32_e32 v59, vcc, 0, v61, vcc
	flat_store_dwordx4 v[58:59], v[28:31] offset:2304
	flat_load_dwordx2 v[28:29], v[14:15] offset:64
	v_cvt_pk_bf16_f32 v54, v78, v79
	v_cvt_pk_bf16_f32 v55, v62, v63
	v_cvt_pk_bf16_f32 v56, v68, v69
	v_cvt_pk_bf16_f32 v57, v70, v71
	v_lshl_add_u64 v[20:21], v[60:61], 0, s[2:3]
	v_permlane32_swap_b32_e32 v54, v56
	v_permlane32_swap_b32_e32 v55, v57
	flat_store_dwordx4 v[20:21], v[54:57] offset:32
	v_pk_mul_f32 v[30:31], v[64:65], v[12:13]
	s_and_b64 vcc, exec, s[38:39]
	v_pk_mul_f32 v[54:55], v[66:67], v[12:13]
	s_cbranch_vccnz .LBB0_104
	v_mov_b32_e32 v60, v229
	v_mov_b32_e32 v61, v230
	v_mov_b32_e32 v58, v231
	v_mov_b32_e32 v59, v228
	v_pk_mul_f32 v[30:31], v[30:31], v[60:61]
	v_pk_mul_f32 v[54:55], v[54:55], v[58:59]
.LBB0_104:
	flat_load_dwordx2 v[56:57], v[14:15] offset:80
	v_pk_mul_f32 v[46:47], v[46:47], v[12:13]
	s_and_b64 vcc, exec, s[38:39]
	v_pk_mul_f32 v[48:49], v[48:49], v[12:13]
	s_cbranch_vccnz .LBB0_106
	v_mov_b32_e32 v62, v233
	v_mov_b32_e32 v63, v234
	v_mov_b32_e32 v60, v235
	v_mov_b32_e32 v61, v232
	v_pk_mul_f32 v[46:47], v[46:47], v[62:63]
	v_pk_mul_f32 v[48:49], v[48:49], v[60:61]
.LBB0_106:
	flat_load_dwordx2 v[58:59], v[14:15] offset:96
	v_pk_mul_f32 v[50:51], v[50:51], v[12:13]
	s_and_b64 vcc, exec, s[38:39]
	v_pk_mul_f32 v[52:53], v[52:53], v[12:13]
	s_cbranch_vccnz .LBB0_108
	v_mov_b32_e32 v64, v237
	v_mov_b32_e32 v65, v238
	v_mov_b32_e32 v62, v239
	v_mov_b32_e32 v63, v236
	v_pk_mul_f32 v[50:51], v[50:51], v[64:65]
	v_pk_mul_f32 v[52:53], v[52:53], v[62:63]
.LBB0_108:
	flat_load_dwordx2 v[60:61], v[14:15] offset:112
	v_pk_mul_f32 v[42:43], v[42:43], v[12:13]
	s_and_b64 vcc, exec, s[38:39]
	v_pk_mul_f32 v[44:45], v[44:45], v[12:13]
	s_cbranch_vccnz .LBB0_110
	v_mov_b32_e32 v66, v245
	v_mov_b32_e32 v67, v246
	v_mov_b32_e32 v64, v247
	v_mov_b32_e32 v65, v244
	v_pk_mul_f32 v[42:43], v[42:43], v[66:67]
	v_pk_mul_f32 v[44:45], v[44:45], v[64:65]
.LBB0_110:
	s_and_b64 vcc, exec, s[38:39]
	s_cbranch_vccnz .Ldiff_epi_b
	global_load_dwordx4 v[212:215], v82, s[42:43] offset:256
	global_load_dwordx4 v[216:219], v82, s[42:43] offset:288
	global_load_dwordx4 v[220:223], v82, s[42:43] offset:320
	global_load_dwordx4 v[224:227], v82, s[42:43] offset:352
	global_load_dwordx4 v[228:231], v82, s[42:43] offset:384
	global_load_dwordx4 v[232:235], v82, s[42:43] offset:416
	global_load_dwordx4 v[236:239], v82, s[42:43] offset:448
	global_load_dwordx4 v[244:247], v82, s[42:43] offset:480
.Ldiff_epi_b:
	s_waitcnt vmcnt(0) lgkmcnt(0)
	v_lshlrev_b32_e32 v62, 16, v58
	v_and_b32_e32 v63, 0xffff0000, v58
	v_lshlrev_b32_e32 v58, 16, v59
	v_and_b32_e32 v59, 0xffff0000, v59
	v_pk_mov_b32 v[64:65], v[52:53], v[50:51] op_sel:[1,0]
	v_pk_mov_b32 v[50:51], v[50:51], v[52:53] op_sel:[1,0]
	v_pk_mul_f32 v[62:63], v[64:65], v[62:63]
	v_pk_mul_f32 v[50:51], v[50:51], v[58:59]
	v_lshlrev_b32_e32 v52, 16, v60
	v_and_b32_e32 v53, 0xffff0000, v60
	v_lshlrev_b32_e32 v58, 16, v61
	v_and_b32_e32 v59, 0xffff0000, v61
	v_lshlrev_b32_e32 v60, 16, v56
	v_and_b32_e32 v61, 0xffff0000, v56
	v_lshlrev_b32_e32 v56, 16, v57
	v_and_b32_e32 v57, 0xffff0000, v57
	v_pk_mov_b32 v[64:65], v[48:49], v[46:47] op_sel:[1,0]
	v_pk_mov_b32 v[46:47], v[46:47], v[48:49] op_sel:[1,0]
	v_lshlrev_b32_e32 v48, 16, v28
	v_pk_mul_f32 v[46:47], v[46:47], v[56:57]
	v_and_b32_e32 v49, 0xffff0000, v28
	v_lshlrev_b32_e32 v28, 16, v29
	v_and_b32_e32 v29, 0xffff0000, v29
	v_pk_mov_b32 v[56:57], v[54:55], v[30:31] op_sel:[1,0]
	v_pk_mov_b32 v[30:31], v[30:31], v[54:55] op_sel:[1,0]
	v_pk_mul_f32 v[60:61], v[64:65], v[60:61]
	v_pk_mul_f32 v[30:31], v[30:31], v[28:29]
	v_pk_mov_b32 v[28:29], v[44:45], v[42:43] op_sel:[1,0]
	v_pk_mul_f32 v[48:49], v[56:57], v[48:49]
	v_pk_mul_f32 v[52:53], v[28:29], v[52:53]
	v_pk_mov_b32 v[28:29], v[42:43], v[44:45] op_sel:[1,0]
	v_cvt_pk_bf16_f32 v42, v62, v63
	v_pk_mul_f32 v[54:55], v[28:29], v[58:59]
	v_cvt_pk_bf16_f32 v28, v48, v49
	v_cvt_pk_bf16_f32 v29, v30, v31
	v_cvt_pk_bf16_f32 v30, v60, v61
	v_cvt_pk_bf16_f32 v31, v46, v47
	s_nop 0
	v_permlane32_swap_b32_e32 v28, v30
	v_permlane32_swap_b32_e32 v29, v31
	flat_store_dwordx4 v[20:21], v[28:31] offset:64
	flat_load_dwordx2 v[28:29], v[14:15] offset:128
	v_cvt_pk_bf16_f32 v43, v50, v51
	v_cvt_pk_bf16_f32 v44, v52, v53
	v_cvt_pk_bf16_f32 v45, v54, v55
	s_nop 0
	v_permlane32_swap_b32_e32 v42, v44
	v_permlane32_swap_b32_e32 v43, v45
	v_pk_mul_f32 v[30:31], v[38:39], v[12:13]
	v_pk_mul_f32 v[38:39], v[40:41], v[12:13]
	s_and_b64 vcc, exec, s[38:39]
	flat_store_dwordx4 v[20:21], v[42:45] offset:96
	s_cbranch_vccnz .LBB0_112
	s_waitcnt vmcnt(0)
	v_mov_b32_e32 v44, v213
	v_mov_b32_e32 v45, v214
	v_mov_b32_e32 v42, v215
	v_mov_b32_e32 v43, v212
	v_pk_mul_f32 v[30:31], v[30:31], v[44:45]
	v_pk_mul_f32 v[38:39], v[38:39], v[42:43]
; DEV int opaque_tid() { int t = threadIdx.x; asm volatile("" : "+v"(t)); return t; }
; template <int NV>
; DEV void attn_store(f32x16 (&o)[NV], float scale_lane, const u16* zrow, u16* arow, const float* vgain  ) {
;   const int lane = opaque_tid() & 63, h = lane >> 5;
; #pragma unroll
;   for (int v = 0; v < NV; ++v) {
;     float ov[16];
; #pragma unroll
;     for (int g4 = 0; g4 < 4; ++g4) {
;       const int f = 32 * v + 8 * g4 + 4 * h;
;       const uint2 zz = *(const uint2*)(zrow + f);
;       float z0 = __uint_as_float(zz.x << 16), z1 = __uint_as_float(zz.x & 0xffff0000u);
;       float z2 = __uint_as_float(zz.y << 16), z3 = __uint_as_float(zz.y & 0xffff0000u);
;       float a0 = o[v][4 * g4] * scale_lane, a1 = o[v][4 * g4 + 1] * scale_lane, a2 = o[v][4 * g4 + 2] * scale_lane,
;             a3 = o[v][4 * g4 + 3] * scale_lane;
;       if (vgain) {
;         const float4 gg = *(const float4*)(vgain + f);
;         a0 *= gg.x; a1 *= gg.y; a2 *= gg.z; a3 *= gg.w;
;       }
;       ov[4 * g4] = a0 * z0; ov[4 * g4 + 1] = a1 * z1; ov[4 * g4 + 2] = a2 * z2; ov[4 * g4 + 3] = a3 * z3;
;     }
;     store_row32(arow + 32 * v, ov, h);
.LBB0_112:
	flat_load_dwordx2 v[40:41], v[14:15] offset:144
	v_pk_mul_f32 v[32:33], v[32:33], v[12:13]
	s_and_b64 vcc, exec, s[38:39]
	v_pk_mul_f32 v[34:35], v[34:35], v[12:13]
	s_cbranch_vccnz .LBB0_114
	v_mov_b32_e32 v46, v217
	v_mov_b32_e32 v47, v218
	v_mov_b32_e32 v44, v219
	v_mov_b32_e32 v45, v216
	v_pk_mul_f32 v[32:33], v[32:33], v[46:47]
	v_pk_mul_f32 v[34:35], v[34:35], v[44:45]
.LBB0_114:
	flat_load_dwordx2 v[42:43], v[14:15] offset:160
	v_pk_mul_f32 v[36:37], v[36:37], v[12:13]
	s_and_b64 vcc, exec, s[38:39]
	v_pk_mul_f32 v[26:27], v[26:27], v[12:13]
	s_cbranch_vccnz .LBB0_116
	v_mov_b32_e32 v48, v221
	v_mov_b32_e32 v49, v222
	v_mov_b32_e32 v46, v223
	v_mov_b32_e32 v47, v220
	v_pk_mul_f32 v[36:37], v[36:37], v[48:49]
	v_pk_mul_f32 v[26:27], v[26:27], v[46:47]
.LBB0_116:
	flat_load_dwordx2 v[44:45], v[14:15] offset:176
	v_pk_mul_f32 v[22:23], v[22:23], v[12:13]
	s_and_b64 vcc, exec, s[38:39]
	v_pk_mul_f32 v[24:25], v[24:25], v[12:13]
	s_cbranch_vccnz .LBB0_118
	v_mov_b32_e32 v50, v225
	v_mov_b32_e32 v51, v226
	v_mov_b32_e32 v48, v227
	v_mov_b32_e32 v49, v224
	v_pk_mul_f32 v[22:23], v[22:23], v[50:51]
	v_pk_mul_f32 v[24:25], v[24:25], v[48:49]
.LBB0_118:
	s_waitcnt vmcnt(0) lgkmcnt(0)
	v_lshlrev_b32_e32 v46, 16, v42
	v_and_b32_e32 v47, 0xffff0000, v42
	v_lshlrev_b32_e32 v42, 16, v43
	v_and_b32_e32 v43, 0xffff0000, v43
	v_pk_mov_b32 v[48:49], v[26:27], v[36:37] op_sel:[1,0]
	v_pk_mov_b32 v[26:27], v[36:37], v[26:27] op_sel:[1,0]
	v_pk_mul_f32 v[46:47], v[48:49], v[46:47]
	v_pk_mul_f32 v[36:37], v[26:27], v[42:43]
	v_lshlrev_b32_e32 v26, 16, v44
	v_and_b32_e32 v27, 0xffff0000, v44
	v_lshlrev_b32_e32 v42, 16, v45
	v_and_b32_e32 v43, 0xffff0000, v45
	v_lshlrev_b32_e32 v44, 16, v40
	v_and_b32_e32 v45, 0xffff0000, v40
	v_lshlrev_b32_e32 v40, 16, v41
	v_and_b32_e32 v41, 0xffff0000, v41
	v_pk_mov_b32 v[48:49], v[34:35], v[32:33] op_sel:[1,0]
	v_pk_mov_b32 v[32:33], v[32:33], v[34:35] op_sel:[1,0]
	v_lshlrev_b32_e32 v34, 16, v28
	v_pk_mul_f32 v[32:33], v[32:33], v[40:41]
	v_and_b32_e32 v35, 0xffff0000, v28
	v_lshlrev_b32_e32 v28, 16, v29
	v_and_b32_e32 v29, 0xffff0000, v29
	v_pk_mov_b32 v[40:41], v[38:39], v[30:31] op_sel:[1,0]
	v_pk_mov_b32 v[30:31], v[30:31], v[38:39] op_sel:[1,0]
	v_pk_mul_f32 v[44:45], v[48:49], v[44:45]
	v_pk_mul_f32 v[34:35], v[40:41], v[34:35]
	v_pk_mul_f32 v[28:29], v[30:31], v[28:29]
	v_pk_mov_b32 v[30:31], v[24:25], v[22:23] op_sel:[1,0]
	v_pk_mov_b32 v[22:23], v[22:23], v[24:25] op_sel:[1,0]
	v_cvt_pk_bf16_f32 v24, v44, v45
	v_pk_mul_f32 v[38:39], v[22:23], v[42:43]
	v_cvt_pk_bf16_f32 v22, v34, v35
	v_cvt_pk_bf16_f32 v23, v28, v29
	v_cvt_pk_bf16_f32 v25, v32, v33
	v_permlane32_swap_b32_e32 v22, v24
	s_nop 0
	v_permlane32_swap_b32_e32 v23, v25
	flat_store_dwordx4 v[20:21], v[22:25] offset:128
	flat_load_dwordx2 v[22:23], v[14:15] offset:192
	v_pk_mul_f32 v[30:31], v[30:31], v[26:27]
	v_cvt_pk_bf16_f32 v26, v46, v47
	v_cvt_pk_bf16_f32 v27, v36, v37
	v_cvt_pk_bf16_f32 v28, v30, v31
	v_cvt_pk_bf16_f32 v29, v38, v39
	s_nop 0
	v_permlane32_swap_b32_e32 v26, v28
	v_permlane32_swap_b32_e32 v27, v29
	v_pk_mul_f32 v[24:25], v[16:17], v[12:13]
	v_pk_mul_f32 v[16:17], v[18:19], v[12:13]
	s_and_b64 vcc, exec, s[38:39]
	flat_store_dwordx4 v[20:21], v[26:29] offset:160
	s_cbranch_vccnz .LBB0_120
	v_pk_mul_f32 v[24:25], v[24:25], v[228:229]
	v_pk_mul_f32 v[16:17], v[16:17], v[230:231]
.LBB0_120:
	flat_load_dwordx2 v[18:19], v[14:15] offset:208
	v_pk_mul_f32 v[26:27], v[0:1], v[12:13]
	s_and_b64 vcc, exec, s[38:39]
	v_pk_mul_f32 v[0:1], v[2:3], v[12:13]
	s_cbranch_vccnz .LBB0_122
	v_pk_mul_f32 v[26:27], v[26:27], v[232:233]
	v_pk_mul_f32 v[0:1], v[0:1], v[234:235]
.LBB0_122:
	flat_load_dwordx2 v[2:3], v[14:15] offset:224
	v_pk_mul_f32 v[28:29], v[8:9], v[12:13]
	s_and_b64 vcc, exec, s[38:39]
	v_pk_mul_f32 v[8:9], v[10:11], v[12:13]
	s_cbranch_vccnz .LBB0_124
	v_pk_mul_f32 v[28:29], v[28:29], v[236:237]
	v_pk_mul_f32 v[8:9], v[8:9], v[238:239]
.LBB0_124:
	flat_load_dwordx2 v[10:11], v[14:15] offset:240
	v_pk_mul_f32 v[4:5], v[4:5], v[12:13]
	s_and_b64 vcc, exec, s[38:39]
	v_pk_mul_f32 v[6:7], v[6:7], v[12:13]
	s_cbranch_vccnz .LBB0_49
	v_mov_b32_e32 v30, v245
	v_mov_b32_e32 v31, v246
	v_mov_b32_e32 v14, v247
	v_mov_b32_e32 v15, v244
	v_pk_mul_f32 v[4:5], v[4:5], v[30:31]
	v_pk_mul_f32 v[6:7], v[6:7], v[14:15]
	s_branch .LBB0_49

; #define MFMA(a, b, c) __builtin_amdgcn_mfma_f32_32x32x16_bf16((a), (b), (c), 0, 0, 0)
; DEV float fast_exp2(float x) { return __builtin_amdgcn_exp2f(x); }
; template <int DQK, int DV, int NKH, int MODE>
; DEV void flash_unit(const FlashArgs& fa, char* smem, f32x16 (&oacc)[DV / 32], float& linv_out) {
;     ...
;       float psum = 0.f;
; #pragma unroll
;       for (int k2 = 0; k2 < 2; ++k2)
; #pragma unroll
;         for (int e = 0; e < 16; ++e) { st[k2][e] = fast_exp2(st[k2][e]); psum += st[k2][e]; }
;       lrun += psum;
;       bf16x8 pf[2][2];
; #pragma unroll
;       for (int k2 = 0; k2 < 2; ++k2)
; #pragma unroll
;         for (int s2 = 0; s2 < 2; ++s2) {
;           uint4 u = make_uint4(pk2(st[k2][8 * s2], st[k2][8 * s2 + 1]), pk2(st[k2][8 * s2 + 2], st[k2][8 * s2 + 3]),
;                                pk2(st[k2][8 * s2 + 4], st[k2][8 * s2 + 5]), pk2(st[k2][8 * s2 + 6], st[k2][8 * s2 + 7]));
;           pf[k2][s2] = __builtin_bit_cast(bf16x8, u);
;         }
; #pragma unroll
;       for (int v = 0; v < NV; ++v)
; #pragma unroll
;         for (int k2 = 0; k2 < 2; ++k2)
; #pragma unroll
;           for (int s2 = 0; s2 < 2; ++s2) {
;             const char* a1 = vb + (k2 * 32 + s2 * 16) * VROW + vhi[v] + vlow0;
;             const char* a2 = vb + (k2 * 32 + s2 * 16 + 8) * VROW + vhi[v] + vlow1;
;             s16x4 lo = __builtin_amdgcn_ds_read_tr16_b64_v4i16((__attribute__((address_space(3))) s16x4*)(a1));
;             s16x4 hi = __builtin_amdgcn_ds_read_tr16_b64_v4i16((__attribute__((address_space(3))) s16x4*)(a2));
;             const bf16x8 vf = __builtin_shufflevector(lo, hi, 0, 1, 2, 3, 4, 5, 6, 7);
;             oacc[v] = MFMA(vf, pf[k2][s2], oacc[v]);
;           }
.LBB0_242:
	v_exp_f32_e32 v96, v96
	v_exp_f32_e32 v97, v97
	v_exp_f32_e32 v98, v98
	v_exp_f32_e32 v99, v99
	v_add_f32_e32 v64, v96, v97
	v_exp_f32_e32 v100, v100
	v_cvt_pk_bf16_f32 v96, v96, v97
	v_exp_f32_e32 v101, v101
	v_add_f32_e32 v64, v64, v98
	v_exp_f32_e32 v102, v102
	v_add_f32_e32 v64, v64, v99
	v_exp_f32_e32 v103, v103
	v_cvt_pk_bf16_f32 v97, v98, v99
	v_add_f32_e32 v64, v64, v100
	v_cvt_pk_bf16_f32 v98, v100, v101
	v_add_f32_e32 v64, v64, v101
	v_cvt_pk_bf16_f32 v99, v102, v103
	v_add_f32_e32 v64, v64, v102
	v_add_f32_e32 v64, v64, v103
	s_waitcnt lgkmcnt(6)
	v_mfma_f32_32x32x16_bf16 v[16:31], v[48:51], v[96:99], v[16:31]
	v_exp_f32_e32 v104, v104
	v_exp_f32_e32 v105, v105
	v_exp_f32_e32 v106, v106
	v_exp_f32_e32 v107, v107
	ds_read_b64_tr_b16 v[48:49], v70 offset:12288
	v_add_f32_e32 v64, v64, v104
	v_add_f32_e32 v64, v64, v105
	v_cvt_pk_bf16_f32 v104, v104, v105
	ds_read_b64_tr_b16 v[50:51], v70 offset:13312
	v_add_f32_e32 v64, v64, v106
	v_cvt_pk_bf16_f32 v105, v106, v107
	v_add_f32_e32 v64, v64, v107
	s_waitcnt lgkmcnt(6)
	v_mfma_f32_32x32x16_bf16 v[0:15], v[52:55], v[96:99], v[0:15]
	v_exp_f32_e32 v108, v108
	v_exp_f32_e32 v109, v109
	v_exp_f32_e32 v110, v110
	v_exp_f32_e32 v111, v111
	ds_read_b64_tr_b16 v[52:53], v71 offset:12288
	v_add_f32_e32 v64, v64, v108
	v_add_f32_e32 v64, v64, v109
	v_cvt_pk_bf16_f32 v106, v108, v109
	ds_read_b64_tr_b16 v[54:55], v71 offset:13312
	v_add_f32_e32 v64, v64, v110
	v_cvt_pk_bf16_f32 v107, v110, v111
	v_add_f32_e32 v64, v64, v111
	s_waitcnt lgkmcnt(6)
	v_mfma_f32_32x32x16_bf16 v[16:31], v[56:59], v[104:107], v[16:31]
	v_exp_f32_e32 v116, v116
	v_exp_f32_e32 v117, v117
	v_exp_f32_e32 v118, v118
	v_exp_f32_e32 v119, v119
	ds_read_b64_tr_b16 v[56:57], v70 offset:14336
	v_add_f32_e32 v64, v64, v116
	v_add_f32_e32 v64, v64, v117
	v_cvt_pk_bf16_f32 v116, v116, v117
	ds_read_b64_tr_b16 v[58:59], v70 offset:15360
	v_add_f32_e32 v64, v64, v118
	v_cvt_pk_bf16_f32 v117, v118, v119
	v_add_f32_e32 v64, v64, v119
	s_waitcnt lgkmcnt(6)
	v_mfma_f32_32x32x16_bf16 v[0:15], v[60:63], v[104:107], v[0:15]
	v_exp_f32_e32 v120, v120
	v_exp_f32_e32 v121, v121
	v_exp_f32_e32 v122, v122
	v_exp_f32_e32 v123, v123
	ds_read_b64_tr_b16 v[60:61], v71 offset:14336
	v_add_f32_e32 v64, v64, v120
	v_add_f32_e32 v64, v64, v121
	v_cvt_pk_bf16_f32 v118, v120, v121
	ds_read_b64_tr_b16 v[62:63], v71 offset:15360
	v_add_f32_e32 v64, v64, v122
	v_cvt_pk_bf16_f32 v119, v122, v123
	v_add_f32_e32 v64, v64, v123
	s_waitcnt lgkmcnt(6)
	v_mfma_f32_32x32x16_bf16 v[16:31], v[48:51], v[116:119], v[16:31]
	v_exp_f32_e32 v124, v124
	v_exp_f32_e32 v125, v125
	v_exp_f32_e32 v126, v126
	v_exp_f32_e32 v127, v127
	v_add_f32_e32 v64, v64, v124
	v_add_f32_e32 v64, v64, v125
	v_cvt_pk_bf16_f32 v124, v124, v125
	v_add_f32_e32 v64, v64, v126
	v_cvt_pk_bf16_f32 v125, v126, v127
	v_add_f32_e32 v64, v64, v127
	s_waitcnt lgkmcnt(4)
	v_mfma_f32_32x32x16_bf16 v[0:15], v[52:55], v[116:119], v[0:15]
	v_exp_f32_e32 v128, v128
	v_exp_f32_e32 v129, v129
	v_exp_f32_e32 v130, v130
	v_exp_f32_e32 v131, v131
	v_add_f32_e32 v64, v64, v128
	v_add_f32_e32 v64, v64, v129
	v_cvt_pk_bf16_f32 v126, v128, v129
	v_add_f32_e32 v64, v64, v130
	v_cvt_pk_bf16_f32 v127, v130, v131
	v_add_f32_e32 v64, v64, v131
	s_waitcnt lgkmcnt(2)
	v_mfma_f32_32x32x16_bf16 v[16:31], v[56:59], v[124:127], v[16:31]
	v_add_f32_e32 v142, v142, v64
	s_waitcnt lgkmcnt(0)
	v_mfma_f32_32x32x16_bf16 v[0:15], v[60:63], v[124:127], v[0:15]

; #define MFMA(a, b, c) __builtin_amdgcn_mfma_f32_32x32x16_bf16((a), (b), (c), 0, 0, 0)
; template <int DQK, int DV, int NKH, int MODE>
; DEV void flash_unit(const FlashArgs& fa, char* smem, f32x16 (&oacc)[DV / 32], float& linv_out) {
;     ...
;           if (s == 0) st[k2] = MFMA(kf, qf[s], negm);
;           else st[k2] = MFMA(kf, qf[s], st[k2]);
;           constexpr int NQK = 2 * NS, EVERY = NQK / LPT;
;           const int m = k2 * NS + s;
;           if ((m + 1) % EVERY == 0 && (m + 1) / EVERY <= LPT) {
;             __builtin_amdgcn_sched_barrier(0);
;             if (pre) issue_piece(it + 3, (m + 1) / EVERY - 1);
;             __builtin_amdgcn_sched_barrier(0);
.LBB0_257:
	v_mfma_f32_32x32x16_bf16 v[48:63], v[96:99], v[88:91], v[32:47]
	v_mfma_f32_32x32x16_bf16 v[48:63], v[100:103], v[80:83], v[48:63]
	v_mfma_f32_32x32x16_bf16 v[48:63], v[104:107], v[84:87], v[48:63]
	v_mfma_f32_32x32x16_bf16 v[48:63], v[108:111], v[92:95], v[48:63]
	s_and_b64 vcc, exec, s[0:1]
	s_cbranch_vccnz .LBB0_259
	s_add_i32 s0, s77, -4
	s_ashr_i32 s1, s0, 31
	s_lshl_b64 s[0:1], s[0:1], 13
	v_add_u32_e32 v98, 0x2000, v116
	v_lshl_add_u64 v[96:97], v[112:113], 0, s[0:1]
	v_readfirstlane_b32 s0, v98
	s_mov_b32 m0, s0
	s_nop 0
	global_load_lds_dwordx4 v[96:97], off

; DEV float fast_exp2(float x) { return __builtin_amdgcn_exp2f(x); }
; template <int DQK, int DV, int NKH, int MODE>
; DEV void flash_unit(const FlashArgs& fa, char* smem, f32x16 (&oacc)[DV / 32], float& linv_out) {
;     ...
;       float rel = st[0][0];
; #pragma unroll
;       for (int e = 1; e < 16; ++e) rel = fmaxf(rel, st[0][e]);
; #pragma unroll
;       for (int e = 0; e < 16; ++e) rel = fmaxf(rel, st[1][e]);
;       rel = half_max(rel);
;       const bool first = (it == 0);
;       if (first || __builtin_amdgcn_ballot_w64(rel > 8.f) != 0) {
;         const float d = first ? rel : fmaxf(rel, 0.f);
;         const float alpha = fast_exp2(-d);
;         mrun += d;
; #pragma unroll
;         for (int k2 = 0; k2 < 2; ++k2)
; #pragma unroll
;           for (int e = 0; e < 16; ++e) st[k2][e] -= d;
; #pragma unroll
;         for (int v = 0; v < NV; ++v)
; #pragma unroll
;           for (int e = 0; e < 16; ++e) oacc[v][e] *= alpha;
; #pragma unroll
;         for (int e = 0; e < 16; ++e) negm[e] = -mrun;
;         lrun *= alpha;
;       }
;     ...
;             const char* a1 = vb + (k2 * 32 + s2 * 16) * VROW + vhi[v] + vlow0;
;             const char* a2 = vb + (k2 * 32 + s2 * 16 + 8) * VROW + vhi[v] + vlow1;
;             s16x4 lo = __builtin_amdgcn_ds_read_tr16_b64_v4i16((__attribute__((address_space(3))) s16x4*)(a1));
;             s16x4 hi = __builtin_amdgcn_ds_read_tr16_b64_v4i16((__attribute__((address_space(3))) s16x4*)(a2));
.LBB0_326:
	v_add3_u32 v70, s76, v139, v141
	v_add3_u32 v71, s76, v140, v141
	ds_read_b64_tr_b16 v[48:49], v70 offset:8192
	ds_read_b64_tr_b16 v[50:51], v70 offset:9216
	ds_read_b64_tr_b16 v[52:53], v71 offset:8192
	ds_read_b64_tr_b16 v[54:55], v71 offset:9216
	ds_read_b64_tr_b16 v[56:57], v70 offset:10240
	ds_read_b64_tr_b16 v[58:59], v70 offset:11264
	ds_read_b64_tr_b16 v[60:61], v71 offset:10240
	ds_read_b64_tr_b16 v[62:63], v71 offset:11264
	v_max3_f32 v72, v96, v97, v98
	v_max3_f32 v73, v99, v100, v101
	v_max3_f32 v74, v102, v103, v104
	v_max3_f32 v75, v105, v106, v107
	v_max3_f32 v72, v72, v108, v109
	v_max3_f32 v73, v73, v110, v111
	v_max3_f32 v74, v74, v116, v117
	v_max3_f32 v75, v75, v118, v119
	v_max3_f32 v72, v72, v120, v121
	v_max3_f32 v73, v73, v122, v123
	v_max3_f32 v74, v74, v124, v125
	v_max3_f32 v75, v75, v126, v127
	v_max3_f32 v72, v72, v128, v129
	v_max3_f32 v73, v73, v130, v131
	v_max3_f32 v72, v72, v73, v74
	v_max_f32_e32 v72, v72, v75
	v_cmp_lt_f32_e32 vcc, s33, v72
	s_cbranch_vccz .LBB0_242
	v_mov_b32_e32 v73, v72
	s_nop 1
	v_permlane32_swap_b32_e32 v72, v73
	v_max_f32_e32 v72, v72, v73
	v_max_f32_e32 v32, 0, v72
	v_exp_f32_e64 v34, -v32
	v_add_f32_e32 v146, v146, v32
	v_pk_add_f32 v[96:97], v[96:97], v[32:33] op_sel_hi:[1,0] neg_lo:[0,1] neg_hi:[0,1]
	v_pk_add_f32 v[98:99], v[98:99], v[32:33] op_sel_hi:[1,0] neg_lo:[0,1] neg_hi:[0,1]
	v_pk_add_f32 v[100:101], v[100:101], v[32:33] op_sel_hi:[1,0] neg_lo:[0,1] neg_hi:[0,1]
	v_pk_add_f32 v[102:103], v[102:103], v[32:33] op_sel_hi:[1,0] neg_lo:[0,1] neg_hi:[0,1]
	v_pk_add_f32 v[104:105], v[104:105], v[32:33] op_sel_hi:[1,0] neg_lo:[0,1] neg_hi:[0,1]
	v_pk_add_f32 v[106:107], v[106:107], v[32:33] op_sel_hi:[1,0] neg_lo:[0,1] neg_hi:[0,1]
	v_pk_add_f32 v[108:109], v[108:109], v[32:33] op_sel_hi:[1,0] neg_lo:[0,1] neg_hi:[0,1]
	v_pk_add_f32 v[110:111], v[110:111], v[32:33] op_sel_hi:[1,0] neg_lo:[0,1] neg_hi:[0,1]
	v_pk_add_f32 v[116:117], v[116:117], v[32:33] op_sel_hi:[1,0] neg_lo:[0,1] neg_hi:[0,1]
	v_pk_add_f32 v[118:119], v[118:119], v[32:33] op_sel_hi:[1,0] neg_lo:[0,1] neg_hi:[0,1]
	v_pk_add_f32 v[120:121], v[120:121], v[32:33] op_sel_hi:[1,0] neg_lo:[0,1] neg_hi:[0,1]
	v_pk_add_f32 v[122:123], v[122:123], v[32:33] op_sel_hi:[1,0] neg_lo:[0,1] neg_hi:[0,1]
	v_pk_add_f32 v[124:125], v[124:125], v[32:33] op_sel_hi:[1,0] neg_lo:[0,1] neg_hi:[0,1]
	v_pk_add_f32 v[126:127], v[126:127], v[32:33] op_sel_hi:[1,0] neg_lo:[0,1] neg_hi:[0,1]
	v_pk_add_f32 v[128:129], v[128:129], v[32:33] op_sel_hi:[1,0] neg_lo:[0,1] neg_hi:[0,1]
	v_pk_add_f32 v[130:131], v[130:131], v[32:33] op_sel_hi:[1,0] neg_lo:[0,1] neg_hi:[0,1]
	v_xor_b32_e32 v32, 0x80000000, v146
	v_pk_mul_f32 v[14:15], v[14:15], v[34:35] op_sel_hi:[1,0]
	v_pk_mul_f32 v[12:13], v[12:13], v[34:35] op_sel_hi:[1,0]
	v_pk_mul_f32 v[10:11], v[10:11], v[34:35] op_sel_hi:[1,0]
	v_pk_mul_f32 v[8:9], v[8:9], v[34:35] op_sel_hi:[1,0]
	v_pk_mul_f32 v[6:7], v[6:7], v[34:35] op_sel_hi:[1,0]
	v_pk_mul_f32 v[4:5], v[4:5], v[34:35] op_sel_hi:[1,0]
	v_pk_mul_f32 v[2:3], v[2:3], v[34:35] op_sel_hi:[1,0]
	v_pk_mul_f32 v[0:1], v[0:1], v[34:35] op_sel_hi:[1,0]
	v_pk_mul_f32 v[30:31], v[30:31], v[34:35] op_sel_hi:[1,0]
	v_pk_mul_f32 v[28:29], v[28:29], v[34:35] op_sel_hi:[1,0]
	v_pk_mul_f32 v[26:27], v[26:27], v[34:35] op_sel_hi:[1,0]
	v_pk_mul_f32 v[24:25], v[24:25], v[34:35] op_sel_hi:[1,0]
	v_pk_mul_f32 v[22:23], v[22:23], v[34:35] op_sel_hi:[1,0]
	v_pk_mul_f32 v[20:21], v[20:21], v[34:35] op_sel_hi:[1,0]
	v_pk_mul_f32 v[18:19], v[18:19], v[34:35] op_sel_hi:[1,0]
	v_pk_mul_f32 v[16:17], v[16:17], v[34:35] op_sel_hi:[1,0]
	v_mul_f32_e32 v142, v142, v34
	v_mov_b32_e32 v33, v32
	v_mov_b32_e32 v34, v32
	v_mov_b32_e32 v35, v32
	v_mov_b32_e32 v36, v32
	v_mov_b32_e32 v37, v32
	v_mov_b32_e32 v38, v32
	v_mov_b32_e32 v39, v32
	v_mov_b32_e32 v40, v32
	v_mov_b32_e32 v41, v32
	v_mov_b32_e32 v42, v32
	v_mov_b32_e32 v43, v32
	v_mov_b32_e32 v44, v32
	v_mov_b32_e32 v45, v32
	v_mov_b32_e32 v46, v32
	v_mov_b32_e32 v47, v32
	s_branch .LBB0_242
